# o3 with nt cache policy on the O1 f32 scratch stores (read back a phase later)
# baseline (speedup 1.0000x reference)
; #define SBAR() __builtin_amdgcn_sched_barrier(0)
; #define PV_READ(S, D0) do { S##0 = tr_read<v_rd_off(D0, 0, 0)>(vb); S##1 = tr_read<v_rd_off(D0, 0, 1)>(vb); S##2 = tr_read<v_rd_off(D0, 1, 0)>(vb); S##3 = tr_read<v_rd_off(D0, 1, 1)>(vb); \
;     S##4 = tr_read<v_rd_off(D0, 2, 0)>(vb); S##5 = tr_read<v_rd_off(D0, 2, 1)>(vb); S##6 = tr_read<v_rd_off(D0, 3, 0)>(vb); S##7 = tr_read<v_rd_off(D0, 3, 1)>(vb); } while (0)
; #define PV_MMA(OD, S) do { OD = __builtin_amdgcn_mfma_f32_32x32x16_bf16(pa0, PV_PK(S##0, S##1), OD, 0, 0, 0); OD = __builtin_amdgcn_mfma_f32_32x32x16_bf16(pa1, PV_PK(S##2, S##3), OD, 0, 0, 0); \
;     OD = __builtin_amdgcn_mfma_f32_32x32x16_bf16(pa2, PV_PK(S##4, S##5), OD, 0, 0, 0); OD = __builtin_amdgcn_mfma_f32_32x32x16_bf16(pa3, PV_PK(S##6, S##7), OD, 0, 0, 0); } while (0)
; #define PV_WAIT() do { asm volatile("s_waitcnt lgkmcnt(0)" ::: "memory"); SBAR(); } while (0)
; __device__ __forceinline__ void finishSM(f32x16& p0, f32x16& p1, float alpha, float& l_reg, bf16x8& pa0, bf16x8& pa1, bf16x8& pa2, bf16x8& pa3) {
; #pragma unroll
;   for (int r = 0; r < 16; ++r) p1[r] = __builtin_amdgcn_exp2f(p1[r]);
;   float ps = 0;
; #pragma unroll
;   for (int r = 0; r < 16; ++r) ps += p0[r];
; #pragma unroll
;   for (int r = 0; r < 16; ++r) ps += p1[r];
;   { auto rr = __builtin_amdgcn_permlane32_swap(__float_as_uint(ps), __float_as_uint(ps), false, false);
;     ps = __uint_as_float(rr[0]) + __uint_as_float(rr[1]); }
;   l_reg = l_reg * alpha + ps;
;     ...
;   PK4(p0, 0, pa0); PK4(p0, 8, pa1); PK4(p1, 0, pa2); PK4(p1, 8, pa3);
; __device__ __forceinline__ void pv_pipe(f32x16* o, int vb, bf16x8 pa0, bf16x8 pa1, bf16x8 pa2, bf16x8 pa3) {
;   s16x4 a0, a1, a2, a3, a4, a5, a6, a7, b0, b1, b2, b3, b4, b5, b6, b7;
;   PV_READ(a, 0); PV_WAIT();
;   PV_READ(b, 1); SBAR(); PV_MMA(o[0], a); PV_WAIT();
;   PV_READ(a, 2); SBAR(); PV_MMA(o[1], b); PV_WAIT();
;   PV_READ(b, 3); SBAR(); PV_MMA(o[2], a); PV_WAIT();
;   PV_MMA(o[3], b);
; }
.LBB0_815:
	v_exp_f32_e32 v82, v98
	v_exp_f32_e32 v83, v99
	v_exp_f32_e32 v84, v100
	v_exp_f32_e32 v85, v101
	v_exp_f32_e32 v86, v102
	v_exp_f32_e32 v98, v66
	v_add_f32_e32 v66, 0, v82
	v_exp_f32_e32 v87, v103
	v_add_f32_e32 v66, v83, v66
	v_exp_f32_e32 v88, v104
	v_add_f32_e32 v66, v84, v66
	v_exp_f32_e32 v89, v105
	v_add_f32_e32 v66, v85, v66
	v_exp_f32_e32 v90, v106
	v_add_f32_e32 v66, v86, v66
	v_exp_f32_e32 v91, v107
	v_add_f32_e32 v66, v87, v66
	v_exp_f32_e32 v92, v108
	v_add_f32_e32 v66, v88, v66
	v_exp_f32_e32 v93, v109
	v_add_f32_e32 v66, v89, v66
	v_exp_f32_e32 v94, v110
	v_add_f32_e32 v66, v90, v66
	v_exp_f32_e32 v95, v111
	v_add_f32_e32 v66, v91, v66
	v_exp_f32_e32 v96, v112
	v_add_f32_e32 v66, v92, v66
	v_exp_f32_e32 v97, v113
	v_add_f32_e32 v66, v93, v66
	v_add_f32_e32 v66, v94, v66
	v_exp_f32_e32 v99, v67
	v_add_f32_e32 v66, v95, v66
	v_exp_f32_e32 v100, v68
	v_add_f32_e32 v66, v96, v66
	v_exp_f32_e32 v101, v69
	v_add_f32_e32 v66, v97, v66
	v_exp_f32_e32 v102, v70
	v_add_f32_e32 v66, v98, v66
	v_exp_f32_e32 v103, v71
	v_add_f32_e32 v66, v99, v66
	v_exp_f32_e32 v104, v72
	v_add_f32_e32 v66, v100, v66
	v_exp_f32_e32 v105, v73
	v_add_f32_e32 v66, v101, v66
	v_exp_f32_e32 v106, v74
	v_add_f32_e32 v66, v102, v66
	v_exp_f32_e32 v107, v75
	v_add_f32_e32 v66, v103, v66
	v_exp_f32_e32 v108, v76
	v_add_f32_e32 v66, v104, v66
	v_exp_f32_e32 v109, v77
	v_add_f32_e32 v66, v105, v66
	v_exp_f32_e32 v110, v78
	v_add_f32_e32 v66, v106, v66
	v_exp_f32_e32 v111, v79
	v_add_f32_e32 v66, v107, v66
	v_exp_f32_e32 v112, v80
	v_add_f32_e32 v66, v108, v66
	v_exp_f32_e32 v113, v81
	v_add_f32_e32 v66, v109, v66
	v_add_f32_e32 v66, v110, v66
	v_add_f32_e32 v66, v111, v66
	v_add_f32_e32 v66, v112, v66
	v_add_f32_e32 v66, v113, v66
	v_mov_b32_e32 v67, v66
	s_nop 1
	v_permlane32_swap_b32_e32 v66, v67
	v_cvt_pk_bf16_f32 v68, v82, v83
	v_cvt_pk_bf16_f32 v69, v84, v85
	v_cvt_pk_bf16_f32 v70, v86, v87
	v_cvt_pk_bf16_f32 v71, v88, v89
	v_cvt_pk_bf16_f32 v72, v90, v91
	v_cvt_pk_bf16_f32 v73, v92, v93
	v_cvt_pk_bf16_f32 v74, v94, v95
	v_cvt_pk_bf16_f32 v75, v96, v97
	v_cvt_pk_bf16_f32 v76, v98, v99
	v_cvt_pk_bf16_f32 v77, v100, v101
	v_cvt_pk_bf16_f32 v78, v102, v103
	v_cvt_pk_bf16_f32 v79, v104, v105
	v_cvt_pk_bf16_f32 v80, v106, v107
	v_cvt_pk_bf16_f32 v81, v108, v109
	v_cvt_pk_bf16_f32 v82, v110, v111
	v_cvt_pk_bf16_f32 v83, v112, v113
	v_permlane32_swap_b32_e32 v68, v70
	v_permlane32_swap_b32_e32 v69, v71
	v_permlane32_swap_b32_e32 v72, v74
	v_permlane32_swap_b32_e32 v73, v75
	v_permlane32_swap_b32_e32 v76, v78
	v_permlane32_swap_b32_e32 v77, v79
	v_permlane32_swap_b32_e32 v80, v82
	v_permlane32_swap_b32_e32 v81, v83
	ds_read_b64_tr_b16 v[84:85], v180 offset:0
	ds_read_b64_tr_b16 v[86:87], v180 offset:0x800
	ds_read_b64_tr_b16 v[88:89], v180 offset:0x1000
	ds_read_b64_tr_b16 v[90:91], v180 offset:0x1800
	ds_read_b64_tr_b16 v[92:93], v180 offset:0x2000
	ds_read_b64_tr_b16 v[94:95], v180 offset:0x2800
	ds_read_b64_tr_b16 v[96:97], v180 offset:0x3000
	ds_read_b64_tr_b16 v[98:99], v180 offset:0x3800
	s_waitcnt lgkmcnt(0)
	ds_read_b64_tr_b16 v[100:101], v180 offset:0x200
	ds_read_b64_tr_b16 v[102:103], v180 offset:0xa00
	ds_read_b64_tr_b16 v[104:105], v180 offset:0x1200
	ds_read_b64_tr_b16 v[106:107], v180 offset:0x1a00
	ds_read_b64_tr_b16 v[108:109], v180 offset:0x2200
	ds_read_b64_tr_b16 v[110:111], v180 offset:0x2a00
	ds_read_b64_tr_b16 v[118:119], v180 offset:0x3200
	ds_read_b64_tr_b16 v[120:121], v180 offset:0x3a00
	s_nop 0
	v_mfma_f32_32x32x16_bf16 v[2:17], v[68:71], v[84:87], v[2:17]
	s_waitcnt lgkmcnt(0)
	v_mfma_f32_32x32x16_bf16 v[2:17], v[72:75], v[88:91], v[2:17]
	v_mfma_f32_32x32x16_bf16 v[2:17], v[76:79], v[92:95], v[2:17]
	v_mfma_f32_32x32x16_bf16 v[2:17], v[80:83], v[96:99], v[2:17]
	ds_read_b64_tr_b16 v[84:85], v180 offset:0x400
	ds_read_b64_tr_b16 v[86:87], v180 offset:0xc00
	ds_read_b64_tr_b16 v[88:89], v180 offset:0x1400
	ds_read_b64_tr_b16 v[90:91], v180 offset:0x1c00
	ds_read_b64_tr_b16 v[92:93], v180 offset:0x2400
	ds_read_b64_tr_b16 v[94:95], v180 offset:0x2c00
	ds_read_b64_tr_b16 v[96:97], v180 offset:0x3400
	ds_read_b64_tr_b16 v[98:99], v180 offset:0x3c00
	v_mfma_f32_32x32x16_bf16 v[50:65], v[68:71], v[100:103], v[50:65]
	s_waitcnt lgkmcnt(0)
	v_mfma_f32_32x32x16_bf16 v[50:65], v[72:75], v[104:107], v[50:65]
	v_mfma_f32_32x32x16_bf16 v[50:65], v[76:79], v[108:111], v[50:65]
	v_mfma_f32_32x32x16_bf16 v[50:65], v[80:83], v[118:121], v[50:65]
	ds_read_b64_tr_b16 v[100:101], v180 offset:0x600
	ds_read_b64_tr_b16 v[102:103], v180 offset:0xe00
	ds_read_b64_tr_b16 v[104:105], v180 offset:0x1600
	ds_read_b64_tr_b16 v[106:107], v180 offset:0x1e00
	ds_read_b64_tr_b16 v[108:109], v180 offset:0x2600
	ds_read_b64_tr_b16 v[110:111], v180 offset:0x2e00
	ds_read_b64_tr_b16 v[118:119], v180 offset:0x3600
	ds_read_b64_tr_b16 v[120:121], v180 offset:0x3e00
	v_mfma_f32_32x32x16_bf16 v[34:49], v[68:71], v[84:87], v[34:49]
	s_waitcnt lgkmcnt(0)
	v_mfma_f32_32x32x16_bf16 v[34:49], v[72:75], v[88:91], v[34:49]
	v_mfma_f32_32x32x16_bf16 v[34:49], v[76:79], v[92:95], v[34:49]
	v_mfma_f32_32x32x16_bf16 v[34:49], v[80:83], v[96:99], v[34:49]
	v_mfma_f32_32x32x16_bf16 v[18:33], v[68:71], v[100:103], v[18:33]
	v_mfma_f32_32x32x16_bf16 v[18:33], v[72:75], v[104:107], v[18:33]
	v_mfma_f32_32x32x16_bf16 v[18:33], v[76:79], v[108:111], v[18:33]
	v_mfma_f32_32x32x16_bf16 v[18:33], v[80:83], v[118:121], v[18:33]
	s_and_saveexec_b64 s[10:11], s[38:39]
	v_add_f32_e32 v68, v114, v115
	v_fmac_f32_e32 v68, v182, v174
	v_add_f32_e32 v66, v66, v67
	v_fmac_f32_e32 v66, v68, v116
	ds_write_b32 v181, v66
	s_or_b64 exec, exec, s[10:11]
	s_waitcnt lgkmcnt(0)
	v_add_u32_e32 v74, s27, v160
	ds_read_b128 v[66:69], v74
	ds_read_b128 v[70:73], v74 offset:32
	s_and_b32 s10, s24, 0xf00
	s_add_u32 s8, s10, s8
	s_addc_u32 s9, 0, s9
	s_waitcnt lgkmcnt(1)
	v_rcp_f32_e32 v75, v66
	v_rcp_f32_e32 v76, v67
	v_rcp_f32_e32 v77, v68
	v_rcp_f32_e32 v78, v69
	s_waitcnt lgkmcnt(0)
	v_rcp_f32_e32 v79, v70
	ds_read_b128 v[66:69], v74 offset:64
	v_rcp_f32_e32 v80, v71
	v_rcp_f32_e32 v81, v72
	v_rcp_f32_e32 v82, v73
	ds_read_b128 v[70:73], v74 offset:96
	v_mov_b32_e32 v74, v0
	s_waitcnt lgkmcnt(0)
	s_barrier
; __device__ __forceinline__ int crow(int r, int hi) { return (r & 3) + 8 * (r >> 2) + 4 * hi; }
; __device__ __forceinline__ int opaque_tid() { int t = threadIdx.x; asm volatile("" : "+v"(t)); return t; }
; template <int MODE> __device__ __forceinline__ void attn_epilogue(char* lds, const att::f32x16 (&o)[4], const float (&rli)[16], float* o1, bf16raw* ob, float lam, float post, const float* gs) {
;     const int tid_ = opaque_tid(); const int lane = tid_ & 63, wave = tid_ >> 6, r32 = lane & 31, hi = lane >> 5;
;     float* st = (float*)(lds + wave * ATT_STAGE);
; #pragma unroll
;     for (int r = 0; r < 16; ++r) { const int orow = att::crow(r, hi);
; #pragma unroll
;         for (int d0 = 0; d0 < 4; ++d0) st[orow * 132 + d0 * 32 + r32] = o[d0][r] * rli[r]; }
;     asm volatile("s_waitcnt lgkmcnt(0)" ::: "memory");
;     float* sr = st + r32 * 132 + 64 * hi;
;     const size_t goff = (size_t)r32 * 1024 + 64 * hi, boff = (size_t)r32 * 2048 + 64 * hi;
	v_mul_f32_e32 v2, v2, v75
	v_lshrrev_b32_e32 v83, 6, v74
	v_and_b32_e32 v84, 31, v74
	v_bfe_u32 v74, v74, 5, 1
	v_mul_lo_u32 v83, v83, s75
	v_add_u32_e32 v83, 0, v83
	v_lshlrev_b32_e32 v85, 2, v84
	v_mul_u32_u24_e32 v86, 0x840, v74
	v_add3_u32 v85, v83, v85, v86
	v_mul_f32_e32 v50, v50, v75
	ds_write2_b32 v85, v2, v50 offset1:32
	v_mul_f32_e32 v2, v34, v75
	v_mul_f32_e32 v18, v18, v75
	ds_write2_b32 v85, v2, v18 offset0:64 offset1:96
	v_mul_f32_e32 v2, v3, v76
	v_mul_f32_e32 v3, v51, v76
	ds_write2_b32 v85, v2, v3 offset0:132 offset1:164
	v_mul_f32_e32 v2, v35, v76
	v_mul_f32_e32 v3, v19, v76
	ds_write2_b32 v85, v2, v3 offset0:196 offset1:228
	v_mul_f32_e32 v2, v4, v77
	v_mul_f32_e32 v3, v52, v77
	v_add_u32_e32 v4, 0x400, v85
	ds_write2_b32 v4, v2, v3 offset0:8 offset1:40
	v_mul_f32_e32 v2, v36, v77
	v_mul_f32_e32 v3, v20, v77
	ds_write2_b32 v4, v2, v3 offset0:72 offset1:104
	v_mul_f32_e32 v2, v5, v78
	v_mul_f32_e32 v3, v53, v78
	ds_write2_b32 v4, v2, v3 offset0:140 offset1:172
	v_mul_f32_e32 v2, v37, v78
	v_mul_f32_e32 v3, v21, v78
	ds_write2_b32 v4, v2, v3 offset0:204 offset1:236
	v_mul_f32_e32 v2, v6, v79
	v_mul_f32_e32 v3, v54, v79
	v_add_u32_e32 v4, 0x1000, v85
	ds_write2_b32 v4, v2, v3 offset0:32 offset1:64
	v_mul_f32_e32 v2, v38, v79
	v_mul_f32_e32 v3, v22, v79
	ds_write2_b32 v4, v2, v3 offset0:96 offset1:128
	v_mul_f32_e32 v2, v7, v80
	v_mul_f32_e32 v3, v55, v80
	ds_write2_b32 v4, v2, v3 offset0:164 offset1:196
	v_mul_f32_e32 v2, v39, v80
	v_mul_f32_e32 v3, v23, v80
	v_add_u32_e32 v4, 0x1200, v85
	v_rcp_f32_e32 v66, v66
	ds_write2_b32 v4, v2, v3 offset0:100 offset1:132
	v_mul_f32_e32 v2, v8, v81
	v_mul_f32_e32 v3, v56, v81
	v_add_u32_e32 v4, 0x1400, v85
	ds_write2_b32 v4, v2, v3 offset0:40 offset1:72
	v_mul_f32_e32 v2, v40, v81
	v_mul_f32_e32 v3, v24, v81
	v_rcp_f32_e32 v67, v67
	ds_write2_b32 v4, v2, v3 offset0:104 offset1:136
	v_mul_f32_e32 v2, v9, v82
	v_mul_f32_e32 v3, v57, v82
	ds_write2_b32 v4, v2, v3 offset0:172 offset1:204
	v_mul_f32_e32 v2, v41, v82
	v_mul_f32_e32 v3, v25, v82
	v_add_u32_e32 v4, 0x1600, v85
	v_rcp_f32_e32 v68, v68
	ds_write2_b32 v4, v2, v3 offset0:108 offset1:140
	v_mul_f32_e32 v2, v10, v66
	v_mul_f32_e32 v3, v58, v66
	v_add_u32_e32 v4, 0x2000, v85
	ds_write2_b32 v4, v2, v3 offset0:64 offset1:96
	v_mul_f32_e32 v2, v42, v66
	v_mul_f32_e32 v3, v26, v66
	v_rcp_f32_e32 v69, v69
	ds_write2_b32 v4, v2, v3 offset0:128 offset1:160
	v_mul_f32_e32 v2, v11, v67
	v_mul_f32_e32 v3, v59, v67
	ds_write2_b32 v4, v2, v3 offset0:196 offset1:228
	v_mul_f32_e32 v2, v43, v67
	v_mul_f32_e32 v3, v27, v67
	v_add_u32_e32 v4, 0x2400, v85
	v_rcp_f32_e32 v70, v70
	ds_write2_b32 v4, v2, v3 offset0:4 offset1:36
	v_mul_f32_e32 v2, v12, v68
	v_mul_f32_e32 v3, v60, v68
	ds_write2_b32 v4, v2, v3 offset0:72 offset1:104
	v_mul_f32_e32 v2, v44, v68
	v_mul_f32_e32 v3, v28, v68
	v_rcp_f32_e32 v71, v71
	ds_write2_b32 v4, v2, v3 offset0:136 offset1:168
	v_mul_f32_e32 v2, v13, v69
	v_mul_f32_e32 v3, v61, v69
	ds_write2_b32 v4, v2, v3 offset0:204 offset1:236
	v_mul_f32_e32 v2, v45, v69
	v_mul_f32_e32 v3, v29, v69
	v_add_u32_e32 v4, 0x2800, v85
	v_rcp_f32_e32 v72, v72
	ds_write2_b32 v4, v2, v3 offset0:12 offset1:44
	v_mul_f32_e32 v2, v14, v70
	v_mul_f32_e32 v3, v62, v70
	v_add_u32_e32 v4, 0x3000, v85
	ds_write2_b32 v4, v2, v3 offset0:96 offset1:128
	v_mul_f32_e32 v2, v46, v70
	v_mul_f32_e32 v3, v30, v70
	v_rcp_f32_e32 v73, v73
	ds_write2_b32 v4, v2, v3 offset0:160 offset1:192
	v_mul_f32_e32 v2, v15, v71
	v_mul_f32_e32 v3, v63, v71
	v_add_u32_e32 v4, 0x3200, v85
	ds_write2_b32 v4, v2, v3 offset0:100 offset1:132
	v_mul_f32_e32 v2, v47, v71
	v_mul_f32_e32 v3, v31, v71
	v_add_u32_e32 v4, 0x3400, v85
	ds_write2_b32 v4, v2, v3 offset0:36 offset1:68
	v_mul_f32_e32 v2, v16, v72
	v_mul_f32_e32 v3, v64, v72
	ds_write2_b32 v4, v2, v3 offset0:104 offset1:136
	v_mul_f32_e32 v2, v48, v72
	v_mul_f32_e32 v3, v32, v72
	ds_write2_b32 v4, v2, v3 offset0:168 offset1:200
	v_mul_f32_e32 v2, v17, v73
	v_mul_f32_e32 v3, v65, v73
	v_add_u32_e32 v4, 0x3600, v85
	ds_write2_b32 v4, v2, v3 offset0:108 offset1:140
	v_mul_f32_e32 v2, v49, v73
	v_mul_f32_e32 v3, v33, v73
	v_add_u32_e32 v4, 0x3800, v85
	ds_write2_b32 v4, v2, v3 offset0:44 offset1:76
	v_mul_u32_u24_e32 v2, 0x210, v74
	v_lshlrev_b32_e32 v5, 4, v84
	v_add3_u32 v4, v83, v2, v5
	v_lshl_add_u64 v[2:3], s[8:9], 0, v[158:159]
	v_lshlrev_b64 v[2:3], 12, v[2:3]
	s_waitcnt lgkmcnt(0)
; template <int MODE> __device__ __forceinline__ void attn_epilogue(char* lds, const att::f32x16 (&o)[4], const float (&rli)[16], float* o1, bf16raw* ob, float lam, float post, const float* gs) {
;     ...
;     float* sr = st + r32 * 132 + 64 * hi;
;     const size_t goff = (size_t)r32 * 1024 + 64 * hi, boff = (size_t)r32 * 2048 + 64 * hi;
;     if constexpr (MODE == 0) {
; #pragma unroll 4
;         for (int j = 0; j < 16; ++j) *(f32x4*)(o1 + goff + 4 * j) = *(const f32x4*)(sr + 4 * j);
	v_lshl_or_b32 v2, s26, 9, v2
	v_lshl_or_b32 v160, v74, 12, v5
	v_lshl_add_u64 v[2:3], v[2:3], 0, v[160:161]
	v_lshl_add_u64 v[2:3], s[0:1], 0, v[2:3]
	s_mov_b32 s98, 0x2000
	s_mov_b32 s99, 0
	ds_read_b128 v[6:9], v4
	ds_read_b128 v[10:13], v4 offset:1056
	ds_read_b128 v[14:17], v4 offset:2112
	ds_read_b128 v[18:21], v4 offset:3168
	s_waitcnt lgkmcnt(3)
	global_store_dwordx4 v[2:3], v[6:9], off offset:-32 nt
	s_nop 0
	v_lshl_add_u64 v[2:3], v[2:3], 0, s[98:99]
	s_waitcnt lgkmcnt(2)
	global_store_dwordx4 v[2:3], v[10:13], off offset:-32 nt
	s_nop 0
	v_lshl_add_u64 v[2:3], v[2:3], 0, s[98:99]
	s_waitcnt lgkmcnt(1)
	global_store_dwordx4 v[2:3], v[14:17], off offset:-32 nt
	s_nop 0
	v_lshl_add_u64 v[2:3], v[2:3], 0, s[98:99]
	s_waitcnt lgkmcnt(0)
	global_store_dwordx4 v[2:3], v[18:21], off offset:-32 nt
	s_nop 0
	v_lshl_add_u64 v[2:3], v[2:3], 0, s[98:99]
	ds_read_b128 v[6:9], v4 offset:4224
	ds_read_b128 v[10:13], v4 offset:5280
	ds_read_b128 v[14:17], v4 offset:6336
	ds_read_b128 v[18:21], v4 offset:7392
	s_waitcnt lgkmcnt(3)
	global_store_dwordx4 v[2:3], v[6:9], off offset:-32 nt
	s_nop 0
	v_lshl_add_u64 v[2:3], v[2:3], 0, s[98:99]
	s_waitcnt lgkmcnt(2)
	global_store_dwordx4 v[2:3], v[10:13], off offset:-32 nt
	s_nop 0
	v_lshl_add_u64 v[2:3], v[2:3], 0, s[98:99]
	s_waitcnt lgkmcnt(1)
	global_store_dwordx4 v[2:3], v[14:17], off offset:-32 nt
	s_nop 0
	v_lshl_add_u64 v[2:3], v[2:3], 0, s[98:99]
	s_waitcnt lgkmcnt(0)
	global_store_dwordx4 v[2:3], v[18:21], off offset:-32 nt
	s_nop 0
	v_lshl_add_u64 v[2:3], v[2:3], 0, s[98:99]
	ds_read_b128 v[6:9], v4 offset:8448
	ds_read_b128 v[10:13], v4 offset:9504
	ds_read_b128 v[14:17], v4 offset:10560
	ds_read_b128 v[18:21], v4 offset:11616
	s_waitcnt lgkmcnt(3)
	global_store_dwordx4 v[2:3], v[6:9], off offset:-32 nt
	s_nop 0
	v_lshl_add_u64 v[2:3], v[2:3], 0, s[98:99]
	s_waitcnt lgkmcnt(2)
	global_store_dwordx4 v[2:3], v[10:13], off offset:-32 nt
	s_nop 0
	v_lshl_add_u64 v[2:3], v[2:3], 0, s[98:99]
	s_waitcnt lgkmcnt(1)
	global_store_dwordx4 v[2:3], v[14:17], off offset:-32 nt
	s_nop 0
	v_lshl_add_u64 v[2:3], v[2:3], 0, s[98:99]
	s_waitcnt lgkmcnt(0)
	global_store_dwordx4 v[2:3], v[18:21], off offset:-32 nt
	s_nop 0
	v_lshl_add_u64 v[2:3], v[2:3], 0, s[98:99]
	ds_read_b128 v[6:9], v4 offset:12672
	ds_read_b128 v[10:13], v4 offset:13728
	ds_read_b128 v[14:17], v4 offset:14784
	ds_read_b128 v[18:21], v4 offset:15840
	s_waitcnt lgkmcnt(3)
	global_store_dwordx4 v[2:3], v[6:9], off offset:-32 nt
	s_nop 0
	v_lshl_add_u64 v[2:3], v[2:3], 0, s[98:99]
	s_waitcnt lgkmcnt(2)
	global_store_dwordx4 v[2:3], v[10:13], off offset:-32 nt
	s_nop 0
	v_lshl_add_u64 v[2:3], v[2:3], 0, s[98:99]
	s_waitcnt lgkmcnt(1)
	global_store_dwordx4 v[2:3], v[14:17], off offset:-32 nt
	s_nop 0
	v_lshl_add_u64 v[2:3], v[2:3], 0, s[98:99]
	s_waitcnt lgkmcnt(0)
	global_store_dwordx4 v[2:3], v[18:21], off offset:-32 nt
	s_nop 0
	v_lshl_add_u64 v[2:3], v[2:3], 0, s[98:99]
	s_add_i32 s4, s4, s73
	s_add_i32 s22, s22, s23
	s_add_i32 s24, s24, s25
	s_cmpk_gt_i32 s4, 0x1ff
	s_barrier
	s_cbranch_scc0 .LBB0_793
	s_branch .LBB0_821
